# GEMM K-loops: counter/pointer updates and exit compare moved in front of the loop-back barrier (branch stays behind it)
# baseline (speedup 1.0000x reference)
; #define PG8_STAGE(bufoff, gbase, voff) do { _Pragma("unroll") for (int _i = 0; _i < 2; ++_i) \
;         __builtin_amdgcn_global_load_lds((const unsigned*)((const char*)(gbase) + (voff)[_i]), (PG8_LAS unsigned*)(lds + (bufoff) + ldsw + _i * 8192), 16, 0, 0); } while (0)
; #define PG8_LDA(dst, b, h) do { _Pragma("unroll") for (int m = 0; m < 4; ++m) _Pragma("unroll") for (int k = 0; k < 2; ++k) dst[m][k] = *(const PG8_LAS bf16x8*)(lds + PG8_SA(b, h) + aoff + m * 2048 + k * 1024); } while (0)
; #define PG8_LDB(dst, b, h) do { _Pragma("unroll") for (int n = 0; n < 2; ++n) _Pragma("unroll") for (int k = 0; k < 2; ++k) dst[n][k] = *(const PG8_LAS bf16x8*)(lds + PG8_SB(b, h) + boff + n * 2048 + k * 1024); } while (0)
; #define PG8_MMA(ai, bj, At, Bt) do { __builtin_amdgcn_s_setprio(1); _Pragma("unroll") for (int m = 0; m < 4; ++m) _Pragma("unroll") for (int n = 0; n < 2; ++n) _Pragma("unroll") for (int k = 0; k < 2; ++k) \
;         acc[ai][bj][m][n] = __builtin_amdgcn_mfma_f32_16x16x32_bf16(Bt[n][k], At[m][k], acc[ai][bj][m][n], 0, 0, 0); __builtin_amdgcn_s_setprio(0); } while (0)
; #define PG8_WAIT_V(n) asm volatile("s_waitcnt vmcnt(" #n ")" ::: "memory")
; #define PG8_WAIT_L(n) asm volatile("s_waitcnt lgkmcnt(" #n ")" ::: "memory")
; #define PG8_BAR __builtin_amdgcn_s_barrier()
; #define PG8_SCHED __builtin_amdgcn_sched_barrier(0)
; template <class Epi, class Sched, bool ALIGN_EPI = false, bool SP2 = false>
; __device__ __forceinline__ void gemm_phase(PG8_LAS unsigned char* lds, const Gemm g, const Sched& S, const Epi& E) {
;     ...
;             const char* a1 = cA + (size_t)(t + 1) * kstep;
;             const char* a2 = last ? nA : cA + (size_t)(t + 2) * kstep; const char* b2 = last ? nB : cB + (size_t)(t + 2) * kstep;
;             const char* a3 = a2 + kstep; const char* b3 = b2 + kstep;
;             if (last && has_next) S.a_ready(nxt);
;             if constexpr (SP2) {
;             PG8_LDB(B0, 0, 0); PG8_LDB(B1, 0, 1); PG8_SCHED; PG8_LDA(At, 0, 0); PG8_STAGE(PG8_SA(1, 1), a1 + hstep, voffA);
;             PG8_WAIT_V(8); PG8_WAIT_L(0); PG8_BAR; PG8_MMA(0, 0, At, B0); PG8_MMA(0, 1, At, B1); PG8_BAR; PG8_SCHED;
;             PG8_LDA(At, 0, 1); PG8_STAGE(PG8_SB(0, 0), b2, voffB); PG8_STAGE(PG8_SB(0, 1), b2 + hstep, voffB); PG8_STAGE(PG8_SA(0, 0), a2, voffA);
.LBB0_607:
	s_add_u32 s30, s28, 0xfffc0080
	s_addc_u32 s31, s29, -1
	s_add_i32 s60, 0, 0x10000
	s_cmp_eq_u32 s59, 12
	s_cselect_b32 s35, s23, s31
	s_cselect_b32 s34, s33, s30
	v_add_u32_e32 v146, s60, v148
	s_cselect_b32 s31, s21, s58
	s_cselect_b32 s30, s56, s57
	s_add_i32 s62, 0, 0x14000
	ds_read_b128 v[142:145], v146
	ds_read_b128 v[152:155], v146 offset:1024
	ds_read_b128 v[156:159], v146 offset:2048
	ds_read_b128 v[160:163], v146 offset:3072
	v_add_u32_e32 v146, s62, v148
	ds_read_b128 v[164:167], v146
	ds_read_b128 v[168:171], v146 offset:1024
	ds_read_b128 v[172:175], v146 offset:2048
	ds_read_b128 v[176:179], v146 offset:3072
	v_lshl_add_u64 v[192:193], s[28:29], 0, v[138:139]
	s_add_i32 m0, s45, 0xc000
	ds_read_b128 v[180:183], v150
	ds_read_b128 v[184:187], v150 offset:1024
	ds_read_b128 v[188:191], v150 offset:2048
	ds_read_b128 v[204:207], v150 offset:3072
	ds_read_b128 v[220:223], v150 offset:4096
	ds_read_b128 v[224:227], v150 offset:5120
	ds_read_b128 v[228:231], v150 offset:6144
	ds_read_b128 v[232:235], v150 offset:7168
	global_load_lds_dwordx4 v[192:193], off
	v_lshl_add_u64 v[192:193], s[28:29], 0, v[140:141]
	s_add_i32 m0, s45, 0xe000
	s_nop 0
	global_load_lds_dwordx4 v[192:193], off
	s_waitcnt vmcnt(8)
	s_waitcnt lgkmcnt(0)
	s_barrier
	s_setprio 1
	s_waitcnt lgkmcnt(0)
	v_mfma_f32_16x16x32_bf16 v[128:131], v[142:145], v[180:183], v[128:131]
	v_mfma_f32_16x16x32_bf16 v[120:123], v[156:159], v[180:183], v[120:123]
	v_mfma_f32_16x16x32_bf16 v[112:115], v[142:145], v[188:191], v[112:115]
	v_mfma_f32_16x16x32_bf16 v[104:107], v[156:159], v[188:191], v[104:107]
	v_mfma_f32_16x16x32_bf16 v[96:99], v[142:145], v[220:223], v[96:99]
	v_mfma_f32_16x16x32_bf16 v[88:91], v[156:159], v[220:223], v[88:91]
	v_mfma_f32_16x16x32_bf16 v[80:83], v[142:145], v[228:231], v[80:83]
	v_mfma_f32_16x16x32_bf16 v[72:75], v[156:159], v[228:231], v[72:75]
	v_mfma_f32_16x16x32_bf16 v[128:131], v[152:155], v[184:187], v[128:131]
	v_mfma_f32_16x16x32_bf16 v[120:123], v[160:163], v[184:187], v[120:123]
	v_mfma_f32_16x16x32_bf16 v[112:115], v[152:155], v[204:207], v[112:115]
	v_mfma_f32_16x16x32_bf16 v[104:107], v[160:163], v[204:207], v[104:107]
	v_mfma_f32_16x16x32_bf16 v[96:99], v[152:155], v[224:227], v[96:99]
	v_mfma_f32_16x16x32_bf16 v[88:91], v[160:163], v[224:227], v[88:91]
	v_mfma_f32_16x16x32_bf16 v[80:83], v[152:155], v[232:235], v[80:83]
	v_mfma_f32_16x16x32_bf16 v[72:75], v[160:163], v[232:235], v[72:75]
	s_setprio 0
	s_setprio 1
	v_mfma_f32_16x16x32_bf16 v[124:127], v[164:167], v[180:183], v[124:127]
	v_mfma_f32_16x16x32_bf16 v[116:119], v[172:175], v[180:183], v[116:119]
	v_mfma_f32_16x16x32_bf16 v[108:111], v[164:167], v[188:191], v[108:111]
	v_mfma_f32_16x16x32_bf16 v[100:103], v[172:175], v[188:191], v[100:103]
	v_mfma_f32_16x16x32_bf16 v[92:95], v[164:167], v[220:223], v[92:95]
	v_mfma_f32_16x16x32_bf16 v[84:87], v[172:175], v[220:223], v[84:87]
	v_mfma_f32_16x16x32_bf16 v[76:79], v[164:167], v[228:231], v[76:79]
	v_mfma_f32_16x16x32_bf16 v[68:71], v[172:175], v[228:231], v[68:71]
	v_mfma_f32_16x16x32_bf16 v[124:127], v[168:171], v[184:187], v[124:127]
	v_mfma_f32_16x16x32_bf16 v[116:119], v[176:179], v[184:187], v[116:119]
	v_mfma_f32_16x16x32_bf16 v[108:111], v[168:171], v[204:207], v[108:111]
	v_mfma_f32_16x16x32_bf16 v[100:103], v[176:179], v[204:207], v[100:103]
	v_mfma_f32_16x16x32_bf16 v[92:95], v[168:171], v[224:227], v[92:95]
	v_mfma_f32_16x16x32_bf16 v[84:87], v[176:179], v[224:227], v[84:87]
	v_mfma_f32_16x16x32_bf16 v[76:79], v[168:171], v[232:235], v[76:79]
	v_mfma_f32_16x16x32_bf16 v[68:71], v[176:179], v[232:235], v[68:71]
	s_setprio 0
	s_barrier
	s_add_i32 s60, s60, s44
	v_lshl_add_u64 v[192:193], s[30:31], 0, v[2:3]
	s_mov_b32 m0, s60
	ds_read_b128 v[180:183], v150 offset:16384
	ds_read_b128 v[184:187], v150 offset:17408
	ds_read_b128 v[188:191], v150 offset:18432
	ds_read_b128 v[204:207], v150 offset:19456
	ds_read_b128 v[220:223], v150 offset:20480
	ds_read_b128 v[224:227], v150 offset:21504
	ds_read_b128 v[228:231], v150 offset:22528
	ds_read_b128 v[232:235], v150 offset:23552
	global_load_lds_dwordx4 v[192:193], off
	s_add_i32 m0, s60, 0x2000
	s_add_u32 s60, s30, 0x40000
	v_lshl_add_u64 v[194:195], s[30:31], 0, v[132:133]
	s_addc_u32 s61, s31, 0
	s_add_i32 s62, s62, s44
	global_load_lds_dwordx4 v[194:195], off
	v_lshl_add_u64 v[196:197], s[60:61], 0, v[2:3]
	s_mov_b32 m0, s62
	v_lshl_add_u64 v[236:237], s[34:35], 0, v[134:135]
	global_load_lds_dwordx4 v[196:197], off
	v_lshl_add_u64 v[196:197], s[60:61], 0, v[132:133]
	s_add_i32 m0, s62, 0x2000
	s_nop 0
	global_load_lds_dwordx4 v[196:197], off
	v_lshl_add_u64 v[196:197], s[34:35], 0, v[136:137]
	s_mov_b32 m0, s45
	s_nop 0
	global_load_lds_dwordx4 v[196:197], off
	s_mov_b32 m0, s46
	s_nop 0
	global_load_lds_dwordx4 v[236:237], off
	s_waitcnt vmcnt(8)
	s_waitcnt lgkmcnt(0)
	s_barrier
; #define PG8_STAGE(bufoff, gbase, voff) do { _Pragma("unroll") for (int _i = 0; _i < 2; ++_i) \
;         __builtin_amdgcn_global_load_lds((const unsigned*)((const char*)(gbase) + (voff)[_i]), (PG8_LAS unsigned*)(lds + (bufoff) + ldsw + _i * 8192), 16, 0, 0); } while (0)
; #define PG8_LDA(dst, b, h) do { _Pragma("unroll") for (int m = 0; m < 4; ++m) _Pragma("unroll") for (int k = 0; k < 2; ++k) dst[m][k] = *(const PG8_LAS bf16x8*)(lds + PG8_SA(b, h) + aoff + m * 2048 + k * 1024); } while (0)
; #define PG8_LDB(dst, b, h) do { _Pragma("unroll") for (int n = 0; n < 2; ++n) _Pragma("unroll") for (int k = 0; k < 2; ++k) dst[n][k] = *(const PG8_LAS bf16x8*)(lds + PG8_SB(b, h) + boff + n * 2048 + k * 1024); } while (0)
; #define PG8_MMA(ai, bj, At, Bt) do { __builtin_amdgcn_s_setprio(1); _Pragma("unroll") for (int m = 0; m < 4; ++m) _Pragma("unroll") for (int n = 0; n < 2; ++n) _Pragma("unroll") for (int k = 0; k < 2; ++k) \
;         acc[ai][bj][m][n] = __builtin_amdgcn_mfma_f32_16x16x32_bf16(Bt[n][k], At[m][k], acc[ai][bj][m][n], 0, 0, 0); __builtin_amdgcn_s_setprio(0); } while (0)
; #define PG8_WAIT_V(n) asm volatile("s_waitcnt vmcnt(" #n ")" ::: "memory")
; #define PG8_WAIT_L(n) asm volatile("s_waitcnt lgkmcnt(" #n ")" ::: "memory")
; #define PG8_BAR __builtin_amdgcn_s_barrier()
; #define PG8_SCHED __builtin_amdgcn_sched_barrier(0)
; template <class Epi, class Sched, bool ALIGN_EPI = false, bool SP2 = false>
; __device__ __forceinline__ void gemm_phase(PG8_LAS unsigned char* lds, const Gemm g, const Sched& S, const Epi& E) {
;     ...
;             PG8_WAIT_V(8); PG8_WAIT_L(0); PG8_BAR; PG8_MMA(1, 0, At, B0); PG8_MMA(1, 1, At, B1); PG8_BAR; PG8_SCHED;
;             PG8_LDB(B0, 1, 0); PG8_LDB(B1, 1, 1); PG8_SCHED; PG8_LDA(At, 1, 0); PG8_STAGE(PG8_SA(0, 1), a2 + hstep, voffA);
;             PG8_WAIT_V(8); PG8_WAIT_L(0); PG8_BAR; PG8_MMA(0, 0, At, B0); PG8_MMA(0, 1, At, B1); PG8_BAR; PG8_SCHED;
	s_setprio 1
	s_waitcnt lgkmcnt(0)
	v_mfma_f32_16x16x32_bf16 v[64:67], v[142:145], v[180:183], v[64:67]
	v_mfma_f32_16x16x32_bf16 v[56:59], v[156:159], v[180:183], v[56:59]
	v_mfma_f32_16x16x32_bf16 v[48:51], v[142:145], v[188:191], v[48:51]
	v_mfma_f32_16x16x32_bf16 v[40:43], v[156:159], v[188:191], v[40:43]
	v_mfma_f32_16x16x32_bf16 v[32:35], v[142:145], v[220:223], v[32:35]
	v_mfma_f32_16x16x32_bf16 v[24:27], v[156:159], v[220:223], v[24:27]
	v_mfma_f32_16x16x32_bf16 v[16:19], v[142:145], v[228:231], v[16:19]
	v_mfma_f32_16x16x32_bf16 v[8:11], v[156:159], v[228:231], v[8:11]
	v_mfma_f32_16x16x32_bf16 v[64:67], v[152:155], v[184:187], v[64:67]
	v_mfma_f32_16x16x32_bf16 v[56:59], v[160:163], v[184:187], v[56:59]
	v_mfma_f32_16x16x32_bf16 v[48:51], v[152:155], v[204:207], v[48:51]
	v_mfma_f32_16x16x32_bf16 v[40:43], v[160:163], v[204:207], v[40:43]
	v_mfma_f32_16x16x32_bf16 v[32:35], v[152:155], v[224:227], v[32:35]
	v_mfma_f32_16x16x32_bf16 v[24:27], v[160:163], v[224:227], v[24:27]
	v_mfma_f32_16x16x32_bf16 v[16:19], v[152:155], v[232:235], v[16:19]
	v_mfma_f32_16x16x32_bf16 v[8:11], v[160:163], v[232:235], v[8:11]
	s_setprio 0
	s_setprio 1
	v_mfma_f32_16x16x32_bf16 v[60:63], v[164:167], v[180:183], v[60:63]
	v_mfma_f32_16x16x32_bf16 v[52:55], v[172:175], v[180:183], v[52:55]
	v_mfma_f32_16x16x32_bf16 v[44:47], v[164:167], v[188:191], v[44:47]
	v_mfma_f32_16x16x32_bf16 v[36:39], v[172:175], v[188:191], v[36:39]
	v_mfma_f32_16x16x32_bf16 v[28:31], v[164:167], v[220:223], v[28:31]
	v_mfma_f32_16x16x32_bf16 v[20:23], v[172:175], v[220:223], v[20:23]
	v_mfma_f32_16x16x32_bf16 v[12:15], v[164:167], v[228:231], v[12:15]
	v_mfma_f32_16x16x32_bf16 v[4:7], v[172:175], v[228:231], v[4:7]
	v_mfma_f32_16x16x32_bf16 v[60:63], v[168:171], v[184:187], v[60:63]
	v_mfma_f32_16x16x32_bf16 v[52:55], v[176:179], v[184:187], v[52:55]
	v_mfma_f32_16x16x32_bf16 v[44:47], v[168:171], v[204:207], v[44:47]
	v_mfma_f32_16x16x32_bf16 v[36:39], v[176:179], v[204:207], v[36:39]
	v_mfma_f32_16x16x32_bf16 v[28:31], v[168:171], v[224:227], v[28:31]
	v_mfma_f32_16x16x32_bf16 v[20:23], v[176:179], v[224:227], v[20:23]
	v_mfma_f32_16x16x32_bf16 v[12:15], v[168:171], v[232:235], v[12:15]
	v_mfma_f32_16x16x32_bf16 v[4:7], v[176:179], v[232:235], v[4:7]
	s_setprio 0
	s_barrier
	s_add_i32 s60, 0, 0x18000
	v_add_u32_e32 v146, s60, v148
	s_add_i32 s61, 0, 0x1c000
	ds_read_b128 v[142:145], v146
	ds_read_b128 v[152:155], v146 offset:1024
	ds_read_b128 v[156:159], v146 offset:2048
	ds_read_b128 v[160:163], v146 offset:3072
	v_add_u32_e32 v146, s61, v148
	ds_read_b128 v[164:167], v146
	ds_read_b128 v[168:171], v146 offset:1024
	ds_read_b128 v[172:175], v146 offset:2048
	ds_read_b128 v[176:179], v146 offset:3072
	s_add_u32 s34, s34, 0x40000
	s_addc_u32 s35, s35, 0
	s_mov_b32 m0, s47
	v_lshl_add_u64 v[238:239], s[34:35], 0, v[136:137]
	ds_read_b128 v[180:183], v150 offset:32768
	ds_read_b128 v[184:187], v150 offset:33792
	ds_read_b128 v[188:191], v150 offset:34816
	ds_read_b128 v[204:207], v150 offset:35840
	ds_read_b128 v[220:223], v150 offset:36864
	ds_read_b128 v[224:227], v150 offset:37888
	ds_read_b128 v[228:231], v150 offset:38912
	ds_read_b128 v[232:235], v150 offset:39936
	global_load_lds_dwordx4 v[238:239], off
	v_lshl_add_u64 v[238:239], s[34:35], 0, v[134:135]
	s_mov_b32 m0, s50
	s_nop 0
	global_load_lds_dwordx4 v[238:239], off
	s_waitcnt vmcnt(8)
	s_waitcnt lgkmcnt(0)
	s_barrier
	s_setprio 1
	s_waitcnt lgkmcnt(0)
	v_mfma_f32_16x16x32_bf16 v[128:131], v[142:145], v[180:183], v[128:131]
	v_mfma_f32_16x16x32_bf16 v[120:123], v[156:159], v[180:183], v[120:123]
	v_mfma_f32_16x16x32_bf16 v[112:115], v[142:145], v[188:191], v[112:115]
	v_mfma_f32_16x16x32_bf16 v[104:107], v[156:159], v[188:191], v[104:107]
	v_mfma_f32_16x16x32_bf16 v[96:99], v[142:145], v[220:223], v[96:99]
	v_mfma_f32_16x16x32_bf16 v[88:91], v[156:159], v[220:223], v[88:91]
	v_mfma_f32_16x16x32_bf16 v[80:83], v[142:145], v[228:231], v[80:83]
	v_mfma_f32_16x16x32_bf16 v[72:75], v[156:159], v[228:231], v[72:75]
	v_mfma_f32_16x16x32_bf16 v[128:131], v[152:155], v[184:187], v[128:131]
	v_mfma_f32_16x16x32_bf16 v[120:123], v[160:163], v[184:187], v[120:123]
	v_mfma_f32_16x16x32_bf16 v[112:115], v[152:155], v[204:207], v[112:115]
	v_mfma_f32_16x16x32_bf16 v[104:107], v[160:163], v[204:207], v[104:107]
	v_mfma_f32_16x16x32_bf16 v[96:99], v[152:155], v[224:227], v[96:99]
	v_mfma_f32_16x16x32_bf16 v[88:91], v[160:163], v[224:227], v[88:91]
	v_mfma_f32_16x16x32_bf16 v[80:83], v[152:155], v[232:235], v[80:83]
	v_mfma_f32_16x16x32_bf16 v[72:75], v[160:163], v[232:235], v[72:75]
	s_setprio 0
	s_setprio 1
	v_mfma_f32_16x16x32_bf16 v[124:127], v[164:167], v[180:183], v[124:127]
	v_mfma_f32_16x16x32_bf16 v[116:119], v[172:175], v[180:183], v[116:119]
	v_mfma_f32_16x16x32_bf16 v[108:111], v[164:167], v[188:191], v[108:111]
	v_mfma_f32_16x16x32_bf16 v[100:103], v[172:175], v[188:191], v[100:103]
	v_mfma_f32_16x16x32_bf16 v[92:95], v[164:167], v[220:223], v[92:95]
	v_mfma_f32_16x16x32_bf16 v[84:87], v[172:175], v[220:223], v[84:87]
	v_mfma_f32_16x16x32_bf16 v[76:79], v[164:167], v[228:231], v[76:79]
	v_mfma_f32_16x16x32_bf16 v[68:71], v[172:175], v[228:231], v[68:71]
	v_mfma_f32_16x16x32_bf16 v[124:127], v[168:171], v[184:187], v[124:127]
	v_mfma_f32_16x16x32_bf16 v[116:119], v[176:179], v[184:187], v[116:119]
	v_mfma_f32_16x16x32_bf16 v[108:111], v[168:171], v[204:207], v[108:111]
	v_mfma_f32_16x16x32_bf16 v[100:103], v[176:179], v[204:207], v[100:103]
	v_mfma_f32_16x16x32_bf16 v[92:95], v[168:171], v[224:227], v[92:95]
	v_mfma_f32_16x16x32_bf16 v[84:87], v[176:179], v[224:227], v[84:87]
	v_mfma_f32_16x16x32_bf16 v[76:79], v[168:171], v[232:235], v[76:79]
	v_mfma_f32_16x16x32_bf16 v[68:71], v[176:179], v[232:235], v[68:71]
	s_setprio 0
	s_barrier
; #define PG8_STAGE(bufoff, gbase, voff) do { _Pragma("unroll") for (int _i = 0; _i < 2; ++_i) \
;         __builtin_amdgcn_global_load_lds((const unsigned*)((const char*)(gbase) + (voff)[_i]), (PG8_LAS unsigned*)(lds + (bufoff) + ldsw + _i * 8192), 16, 0, 0); } while (0)
; #define PG8_LDA(dst, b, h) do { _Pragma("unroll") for (int m = 0; m < 4; ++m) _Pragma("unroll") for (int k = 0; k < 2; ++k) dst[m][k] = *(const PG8_LAS bf16x8*)(lds + PG8_SA(b, h) + aoff + m * 2048 + k * 1024); } while (0)
; #define PG8_MMA(ai, bj, At, Bt) do { __builtin_amdgcn_s_setprio(1); _Pragma("unroll") for (int m = 0; m < 4; ++m) _Pragma("unroll") for (int n = 0; n < 2; ++n) _Pragma("unroll") for (int k = 0; k < 2; ++k) \
;         acc[ai][bj][m][n] = __builtin_amdgcn_mfma_f32_16x16x32_bf16(Bt[n][k], At[m][k], acc[ai][bj][m][n], 0, 0, 0); __builtin_amdgcn_s_setprio(0); } while (0)
; #define PG8_WAIT_V(n) asm volatile("s_waitcnt vmcnt(" #n ")" ::: "memory")
; #define PG8_WAIT_L(n) asm volatile("s_waitcnt lgkmcnt(" #n ")" ::: "memory")
; #define PG8_BAR __builtin_amdgcn_s_barrier()
; #define PG8_SCHED __builtin_amdgcn_sched_barrier(0)
; template <class Epi, class Sched, bool ALIGN_EPI = false, bool SP2 = false>
; __device__ __forceinline__ void gemm_phase(PG8_LAS unsigned char* lds, const Gemm g, const Sched& S, const Epi& E) {
;     ...
;             PG8_WAIT_V(8); PG8_WAIT_L(0); PG8_BAR; PG8_MMA(0, 0, At, B0); PG8_MMA(0, 1, At, B1); PG8_BAR; PG8_SCHED;
;             PG8_LDA(At, 1, 1); PG8_STAGE(PG8_SB(1, 0), b3, voffB); PG8_STAGE(PG8_SB(1, 1), b3 + hstep, voffB); PG8_STAGE(PG8_SA(1, 0), a3, voffA);
;             PG8_WAIT_V(8); PG8_WAIT_L(0); PG8_BAR; PG8_MMA(1, 0, At, B0); PG8_MMA(1, 1, At, B1); PG8_BAR; PG8_SCHED;
	s_add_i32 s34, s60, s44
	v_lshl_add_u64 v[192:193], v[192:193], 0, s[92:93]
	s_mov_b32 m0, s34
	ds_read_b128 v[180:183], v150 offset:49152
	ds_read_b128 v[184:187], v150 offset:50176
	ds_read_b128 v[188:191], v150 offset:51200
	ds_read_b128 v[204:207], v150 offset:52224
	ds_read_b128 v[220:223], v150 offset:53248
	ds_read_b128 v[224:227], v150 offset:54272
	ds_read_b128 v[228:231], v150 offset:55296
	ds_read_b128 v[232:235], v150 offset:56320
	global_load_lds_dwordx4 v[192:193], off
	s_add_i32 m0, s34, 0x2000
	s_add_u32 s30, s30, 0x40080
	v_lshl_add_u64 v[192:193], v[194:195], 0, s[92:93]
	s_addc_u32 s31, s31, 0
	s_add_i32 s34, s61, s44
	global_load_lds_dwordx4 v[192:193], off
	v_lshl_add_u64 v[192:193], s[30:31], 0, v[2:3]
	s_mov_b32 m0, s34
	s_nop 0
	global_load_lds_dwordx4 v[192:193], off
	v_lshl_add_u64 v[192:193], s[30:31], 0, v[132:133]
	s_add_i32 m0, s34, 0x2000
	s_nop 0
	global_load_lds_dwordx4 v[192:193], off
	v_lshl_add_u64 v[192:193], v[196:197], 0, s[92:93]
	s_mov_b32 m0, s51
	s_nop 0
	global_load_lds_dwordx4 v[192:193], off
	v_lshl_add_u64 v[192:193], v[236:237], 0, s[92:93]
	s_mov_b32 m0, s52
	s_nop 0
	global_load_lds_dwordx4 v[192:193], off
	s_waitcnt vmcnt(8)
	s_waitcnt lgkmcnt(0)
	s_barrier
	s_setprio 1
	s_waitcnt lgkmcnt(0)
	v_mfma_f32_16x16x32_bf16 v[64:67], v[142:145], v[180:183], v[64:67]
	v_mfma_f32_16x16x32_bf16 v[56:59], v[156:159], v[180:183], v[56:59]
	v_mfma_f32_16x16x32_bf16 v[48:51], v[142:145], v[188:191], v[48:51]
	v_mfma_f32_16x16x32_bf16 v[40:43], v[156:159], v[188:191], v[40:43]
	v_mfma_f32_16x16x32_bf16 v[32:35], v[142:145], v[220:223], v[32:35]
	v_mfma_f32_16x16x32_bf16 v[24:27], v[156:159], v[220:223], v[24:27]
	v_mfma_f32_16x16x32_bf16 v[16:19], v[142:145], v[228:231], v[16:19]
	v_mfma_f32_16x16x32_bf16 v[8:11], v[156:159], v[228:231], v[8:11]
	v_mfma_f32_16x16x32_bf16 v[64:67], v[152:155], v[184:187], v[64:67]
	v_mfma_f32_16x16x32_bf16 v[56:59], v[160:163], v[184:187], v[56:59]
	v_mfma_f32_16x16x32_bf16 v[48:51], v[152:155], v[204:207], v[48:51]
	v_mfma_f32_16x16x32_bf16 v[40:43], v[160:163], v[204:207], v[40:43]
	v_mfma_f32_16x16x32_bf16 v[32:35], v[152:155], v[224:227], v[32:35]
	v_mfma_f32_16x16x32_bf16 v[24:27], v[160:163], v[224:227], v[24:27]
	v_mfma_f32_16x16x32_bf16 v[16:19], v[152:155], v[232:235], v[16:19]
	v_mfma_f32_16x16x32_bf16 v[8:11], v[160:163], v[232:235], v[8:11]
	s_setprio 0
	s_setprio 1
	v_mfma_f32_16x16x32_bf16 v[60:63], v[164:167], v[180:183], v[60:63]
	v_mfma_f32_16x16x32_bf16 v[52:55], v[172:175], v[180:183], v[52:55]
	v_mfma_f32_16x16x32_bf16 v[44:47], v[164:167], v[188:191], v[44:47]
	v_mfma_f32_16x16x32_bf16 v[36:39], v[172:175], v[188:191], v[36:39]
	v_mfma_f32_16x16x32_bf16 v[28:31], v[164:167], v[220:223], v[28:31]
	v_mfma_f32_16x16x32_bf16 v[20:23], v[172:175], v[220:223], v[20:23]
	v_mfma_f32_16x16x32_bf16 v[12:15], v[164:167], v[228:231], v[12:15]
	v_mfma_f32_16x16x32_bf16 v[4:7], v[172:175], v[228:231], v[4:7]
	v_mfma_f32_16x16x32_bf16 v[60:63], v[168:171], v[184:187], v[60:63]
	v_mfma_f32_16x16x32_bf16 v[52:55], v[176:179], v[184:187], v[52:55]
	v_mfma_f32_16x16x32_bf16 v[44:47], v[168:171], v[204:207], v[44:47]
	v_mfma_f32_16x16x32_bf16 v[36:39], v[176:179], v[204:207], v[36:39]
	v_mfma_f32_16x16x32_bf16 v[28:31], v[168:171], v[224:227], v[28:31]
	v_mfma_f32_16x16x32_bf16 v[20:23], v[176:179], v[224:227], v[20:23]
	v_mfma_f32_16x16x32_bf16 v[12:15], v[168:171], v[232:235], v[12:15]
	v_mfma_f32_16x16x32_bf16 v[4:7], v[176:179], v[232:235], v[4:7]
	s_add_i32 s59, s59, 2
	s_add_u32 s28, s28, 0x100
	s_addc_u32 s29, s29, 0
	s_add_u32 s57, s57, 0x100
	s_addc_u32 s58, s58, 0
	s_cmp_gt_u32 s59, 13
	s_setprio 0
	s_barrier
	s_cbranch_scc0 .LBB0_607
	s_and_b64 vcc, exec, s[18:19]
	s_cbranch_vccz .LBB0_610
	s_barrier

; #define PG8_STAGE(bufoff, gbase, voff) do { _Pragma("unroll") for (int _i = 0; _i < 2; ++_i) \
;         __builtin_amdgcn_global_load_lds((const unsigned*)((const char*)(gbase) + (voff)[_i]), (PG8_LAS unsigned*)(lds + (bufoff) + ldsw + _i * 8192), 16, 0, 0); } while (0)
; #define PG8_LDA(dst, b, h) do { _Pragma("unroll") for (int m = 0; m < 4; ++m) _Pragma("unroll") for (int k = 0; k < 2; ++k) dst[m][k] = *(const PG8_LAS bf16x8*)(lds + PG8_SA(b, h) + aoff + m * 2048 + k * 1024); } while (0)
; #define PG8_LDB(dst, b, h) do { _Pragma("unroll") for (int n = 0; n < 2; ++n) _Pragma("unroll") for (int k = 0; k < 2; ++k) dst[n][k] = *(const PG8_LAS bf16x8*)(lds + PG8_SB(b, h) + boff + n * 2048 + k * 1024); } while (0)
; #define PG8_MMA(ai, bj, At, Bt) do { __builtin_amdgcn_s_setprio(1); _Pragma("unroll") for (int m = 0; m < 4; ++m) _Pragma("unroll") for (int n = 0; n < 2; ++n) _Pragma("unroll") for (int k = 0; k < 2; ++k) \
;         acc[ai][bj][m][n] = __builtin_amdgcn_mfma_f32_16x16x32_bf16(Bt[n][k], At[m][k], acc[ai][bj][m][n], 0, 0, 0); __builtin_amdgcn_s_setprio(0); } while (0)
; #define PG8_WAIT_V(n) asm volatile("s_waitcnt vmcnt(" #n ")" ::: "memory")
; #define PG8_WAIT_L(n) asm volatile("s_waitcnt lgkmcnt(" #n ")" ::: "memory")
; #define PG8_BAR __builtin_amdgcn_s_barrier()
; #define PG8_SCHED __builtin_amdgcn_sched_barrier(0)
; template <class Epi, class Sched, bool ALIGN_EPI = false, bool SP2 = false>
; __device__ __forceinline__ void gemm_phase(PG8_LAS unsigned char* lds, const Gemm g, const Sched& S, const Epi& E) {
;     ...
;             const char* a1 = cA + (size_t)(t + 1) * kstep;
;             const char* a2 = last ? nA : cA + (size_t)(t + 2) * kstep; const char* b2 = last ? nB : cB + (size_t)(t + 2) * kstep;
;             const char* a3 = a2 + kstep; const char* b3 = b2 + kstep;
;             if (last && has_next) S.a_ready(nxt);
;             if constexpr (SP2) {
;             PG8_LDB(B0, 0, 0); PG8_LDB(B1, 0, 1); PG8_SCHED; PG8_LDA(At, 0, 0); PG8_STAGE(PG8_SA(1, 1), a1 + hstep, voffA);
;             PG8_WAIT_V(8); PG8_WAIT_L(0); PG8_BAR; PG8_MMA(0, 0, At, B0); PG8_MMA(0, 1, At, B1); PG8_BAR; PG8_SCHED;
;             PG8_LDA(At, 0, 1); PG8_STAGE(PG8_SB(0, 0), b2, voffB); PG8_STAGE(PG8_SB(0, 1), b2 + hstep, voffB); PG8_STAGE(PG8_SA(0, 0), a2, voffA);
.LBB0_638:
	s_add_i32 s55, s28, 2
	s_add_u32 s56, s26, 0x80
	s_addc_u32 s29, s27, 0
	s_add_i32 s58, 0, 0x10000
	s_cmp_eq_u32 s47, s28
	s_cselect_b32 s29, s7, s29
	s_cselect_b32 s28, s6, s56
	s_cselect_b32 s57, s25, s54
	s_cselect_b32 s56, s24, s33
	s_add_i32 s59, 0, 0x14000
	v_add_u32_e32 v158, s58, v147
	v_add_u32_e32 v174, s59, v147
	ds_read_b128 v[142:145], v158
	ds_read_b128 v[150:153], v158 offset:1024
	ds_read_b128 v[154:157], v158 offset:2048
	ds_read_b128 v[158:161], v158 offset:3072
	ds_read_b128 v[162:165], v174
	ds_read_b128 v[166:169], v174 offset:1024
	ds_read_b128 v[170:173], v174 offset:2048
	ds_read_b128 v[174:177], v174 offset:3072
	v_lshl_add_u64 v[194:195], s[26:27], 0, v[138:139]
	s_add_i32 m0, s34, 0xc000
	ds_read_b128 v[178:181], v149
	ds_read_b128 v[182:185], v149 offset:1024
	ds_read_b128 v[186:189], v149 offset:2048
	ds_read_b128 v[190:193], v149 offset:3072
	ds_read_b128 v[204:207], v149 offset:4096
	ds_read_b128 v[220:223], v149 offset:5120
	ds_read_b128 v[224:227], v149 offset:6144
	ds_read_b128 v[228:231], v149 offset:7168
	global_load_lds_dwordx4 v[194:195], off
	v_lshl_add_u64 v[194:195], s[26:27], 0, v[140:141]
	s_add_i32 m0, s34, 0xe000
	s_nop 0
	global_load_lds_dwordx4 v[194:195], off
	s_waitcnt vmcnt(8)
	s_waitcnt lgkmcnt(0)
	s_barrier
	s_setprio 1
	s_waitcnt lgkmcnt(0)
	v_mfma_f32_16x16x32_bf16 v[128:131], v[142:145], v[178:181], v[128:131]
	v_mfma_f32_16x16x32_bf16 v[124:127], v[154:157], v[178:181], v[124:127]
	v_mfma_f32_16x16x32_bf16 v[112:115], v[142:145], v[186:189], v[112:115]
	v_mfma_f32_16x16x32_bf16 v[108:111], v[154:157], v[186:189], v[108:111]
	v_mfma_f32_16x16x32_bf16 v[96:99], v[142:145], v[204:207], v[96:99]
	v_mfma_f32_16x16x32_bf16 v[92:95], v[154:157], v[204:207], v[92:95]
	v_mfma_f32_16x16x32_bf16 v[80:83], v[142:145], v[224:227], v[80:83]
	v_mfma_f32_16x16x32_bf16 v[76:79], v[154:157], v[224:227], v[76:79]
	v_mfma_f32_16x16x32_bf16 v[128:131], v[150:153], v[182:185], v[128:131]
	v_mfma_f32_16x16x32_bf16 v[124:127], v[158:161], v[182:185], v[124:127]
	v_mfma_f32_16x16x32_bf16 v[112:115], v[150:153], v[190:193], v[112:115]
	v_mfma_f32_16x16x32_bf16 v[108:111], v[158:161], v[190:193], v[108:111]
	v_mfma_f32_16x16x32_bf16 v[96:99], v[150:153], v[220:223], v[96:99]
	v_mfma_f32_16x16x32_bf16 v[92:95], v[158:161], v[220:223], v[92:95]
	v_mfma_f32_16x16x32_bf16 v[80:83], v[150:153], v[228:231], v[80:83]
	v_mfma_f32_16x16x32_bf16 v[76:79], v[158:161], v[228:231], v[76:79]
	s_setprio 0
	s_setprio 1
	v_mfma_f32_16x16x32_bf16 v[120:123], v[162:165], v[178:181], v[120:123]
	v_mfma_f32_16x16x32_bf16 v[116:119], v[170:173], v[178:181], v[116:119]
	v_mfma_f32_16x16x32_bf16 v[104:107], v[162:165], v[186:189], v[104:107]
	v_mfma_f32_16x16x32_bf16 v[100:103], v[170:173], v[186:189], v[100:103]
	v_mfma_f32_16x16x32_bf16 v[88:91], v[162:165], v[204:207], v[88:91]
	v_mfma_f32_16x16x32_bf16 v[84:87], v[170:173], v[204:207], v[84:87]
	v_mfma_f32_16x16x32_bf16 v[72:75], v[162:165], v[224:227], v[72:75]
	v_mfma_f32_16x16x32_bf16 v[68:71], v[170:173], v[224:227], v[68:71]
	v_mfma_f32_16x16x32_bf16 v[120:123], v[166:169], v[182:185], v[120:123]
	v_mfma_f32_16x16x32_bf16 v[116:119], v[174:177], v[182:185], v[116:119]
	v_mfma_f32_16x16x32_bf16 v[104:107], v[166:169], v[190:193], v[104:107]
	v_mfma_f32_16x16x32_bf16 v[100:103], v[174:177], v[190:193], v[100:103]
	v_mfma_f32_16x16x32_bf16 v[88:91], v[166:169], v[220:223], v[88:91]
	v_mfma_f32_16x16x32_bf16 v[84:87], v[174:177], v[220:223], v[84:87]
	v_mfma_f32_16x16x32_bf16 v[72:75], v[166:169], v[228:231], v[72:75]
	v_mfma_f32_16x16x32_bf16 v[68:71], v[174:177], v[228:231], v[68:71]
	s_setprio 0
	s_barrier
	s_add_i32 s58, s58, s31
	v_lshl_add_u64 v[194:195], s[56:57], 0, v[2:3]
	s_mov_b32 m0, s58
	ds_read_b128 v[178:181], v149 offset:16384
	ds_read_b128 v[182:185], v149 offset:17408
	ds_read_b128 v[186:189], v149 offset:18432
	ds_read_b128 v[190:193], v149 offset:19456
	ds_read_b128 v[204:207], v149 offset:20480
	ds_read_b128 v[220:223], v149 offset:21504
	ds_read_b128 v[224:227], v149 offset:22528
	ds_read_b128 v[228:231], v149 offset:23552
	global_load_lds_dwordx4 v[194:195], off
	s_add_i32 m0, s58, 0x2000
	v_lshl_add_u64 v[196:197], s[56:57], 0, v[132:133]
	s_add_u32 s56, s56, s10
	s_addc_u32 s57, s57, 0
	s_add_i32 s58, s59, s31
	global_load_lds_dwordx4 v[196:197], off
	v_lshl_add_u64 v[232:233], s[56:57], 0, v[2:3]
	s_mov_b32 m0, s58
	v_lshl_add_u64 v[234:235], s[56:57], 0, v[132:133]
	global_load_lds_dwordx4 v[232:233], off
	s_add_i32 m0, s58, 0x2000
	v_lshl_add_u64 v[236:237], s[28:29], 0, v[136:137]
	global_load_lds_dwordx4 v[234:235], off
	s_mov_b32 m0, s34
	v_lshl_add_u64 v[238:239], s[28:29], 0, v[134:135]
	global_load_lds_dwordx4 v[236:237], off
	s_mov_b32 m0, s35
	s_nop 0
	global_load_lds_dwordx4 v[238:239], off
	s_waitcnt vmcnt(8)
	s_waitcnt lgkmcnt(0)
	s_barrier
; #define PG8_STAGE(bufoff, gbase, voff) do { _Pragma("unroll") for (int _i = 0; _i < 2; ++_i) \
;         __builtin_amdgcn_global_load_lds((const unsigned*)((const char*)(gbase) + (voff)[_i]), (PG8_LAS unsigned*)(lds + (bufoff) + ldsw + _i * 8192), 16, 0, 0); } while (0)
; #define PG8_LDA(dst, b, h) do { _Pragma("unroll") for (int m = 0; m < 4; ++m) _Pragma("unroll") for (int k = 0; k < 2; ++k) dst[m][k] = *(const PG8_LAS bf16x8*)(lds + PG8_SA(b, h) + aoff + m * 2048 + k * 1024); } while (0)
; #define PG8_LDB(dst, b, h) do { _Pragma("unroll") for (int n = 0; n < 2; ++n) _Pragma("unroll") for (int k = 0; k < 2; ++k) dst[n][k] = *(const PG8_LAS bf16x8*)(lds + PG8_SB(b, h) + boff + n * 2048 + k * 1024); } while (0)
; #define PG8_MMA(ai, bj, At, Bt) do { __builtin_amdgcn_s_setprio(1); _Pragma("unroll") for (int m = 0; m < 4; ++m) _Pragma("unroll") for (int n = 0; n < 2; ++n) _Pragma("unroll") for (int k = 0; k < 2; ++k) \
;         acc[ai][bj][m][n] = __builtin_amdgcn_mfma_f32_16x16x32_bf16(Bt[n][k], At[m][k], acc[ai][bj][m][n], 0, 0, 0); __builtin_amdgcn_s_setprio(0); } while (0)
; #define PG8_WAIT_V(n) asm volatile("s_waitcnt vmcnt(" #n ")" ::: "memory")
; #define PG8_WAIT_L(n) asm volatile("s_waitcnt lgkmcnt(" #n ")" ::: "memory")
; #define PG8_BAR __builtin_amdgcn_s_barrier()
; #define PG8_SCHED __builtin_amdgcn_sched_barrier(0)
; template <class Epi, class Sched, bool ALIGN_EPI = false, bool SP2 = false>
; __device__ __forceinline__ void gemm_phase(PG8_LAS unsigned char* lds, const Gemm g, const Sched& S, const Epi& E) {
;     ...
;             PG8_WAIT_V(8); PG8_WAIT_L(0); PG8_BAR; PG8_MMA(1, 0, At, B0); PG8_MMA(1, 1, At, B1); PG8_BAR; PG8_SCHED;
;             PG8_LDB(B0, 1, 0); PG8_LDB(B1, 1, 1); PG8_SCHED; PG8_LDA(At, 1, 0); PG8_STAGE(PG8_SA(0, 1), a2 + hstep, voffA);
;             PG8_WAIT_V(8); PG8_WAIT_L(0); PG8_BAR; PG8_MMA(0, 0, At, B0); PG8_MMA(0, 1, At, B1); PG8_BAR; PG8_SCHED;
	s_setprio 1
	s_waitcnt lgkmcnt(0)
	v_mfma_f32_16x16x32_bf16 v[64:67], v[142:145], v[178:181], v[64:67]
	v_mfma_f32_16x16x32_bf16 v[60:63], v[154:157], v[178:181], v[60:63]
	v_mfma_f32_16x16x32_bf16 v[48:51], v[142:145], v[186:189], v[48:51]
	v_mfma_f32_16x16x32_bf16 v[44:47], v[154:157], v[186:189], v[44:47]
	v_mfma_f32_16x16x32_bf16 v[32:35], v[142:145], v[204:207], v[32:35]
	v_mfma_f32_16x16x32_bf16 v[28:31], v[154:157], v[204:207], v[28:31]
	v_mfma_f32_16x16x32_bf16 v[16:19], v[142:145], v[224:227], v[16:19]
	v_mfma_f32_16x16x32_bf16 v[12:15], v[154:157], v[224:227], v[12:15]
	v_mfma_f32_16x16x32_bf16 v[64:67], v[150:153], v[182:185], v[64:67]
	v_mfma_f32_16x16x32_bf16 v[60:63], v[158:161], v[182:185], v[60:63]
	v_mfma_f32_16x16x32_bf16 v[48:51], v[150:153], v[190:193], v[48:51]
	v_mfma_f32_16x16x32_bf16 v[44:47], v[158:161], v[190:193], v[44:47]
	v_mfma_f32_16x16x32_bf16 v[32:35], v[150:153], v[220:223], v[32:35]
	v_mfma_f32_16x16x32_bf16 v[28:31], v[158:161], v[220:223], v[28:31]
	v_mfma_f32_16x16x32_bf16 v[16:19], v[150:153], v[228:231], v[16:19]
	v_mfma_f32_16x16x32_bf16 v[12:15], v[158:161], v[228:231], v[12:15]
	s_setprio 0
	s_setprio 1
	v_mfma_f32_16x16x32_bf16 v[56:59], v[162:165], v[178:181], v[56:59]
	v_mfma_f32_16x16x32_bf16 v[52:55], v[170:173], v[178:181], v[52:55]
	v_mfma_f32_16x16x32_bf16 v[40:43], v[162:165], v[186:189], v[40:43]
	v_mfma_f32_16x16x32_bf16 v[36:39], v[170:173], v[186:189], v[36:39]
	v_mfma_f32_16x16x32_bf16 v[24:27], v[162:165], v[204:207], v[24:27]
	v_mfma_f32_16x16x32_bf16 v[20:23], v[170:173], v[204:207], v[20:23]
	v_mfma_f32_16x16x32_bf16 v[8:11], v[162:165], v[224:227], v[8:11]
	v_mfma_f32_16x16x32_bf16 v[4:7], v[170:173], v[224:227], v[4:7]
	v_mfma_f32_16x16x32_bf16 v[56:59], v[166:169], v[182:185], v[56:59]
	v_mfma_f32_16x16x32_bf16 v[52:55], v[174:177], v[182:185], v[52:55]
	v_mfma_f32_16x16x32_bf16 v[40:43], v[166:169], v[190:193], v[40:43]
	v_mfma_f32_16x16x32_bf16 v[36:39], v[174:177], v[190:193], v[36:39]
	v_mfma_f32_16x16x32_bf16 v[24:27], v[166:169], v[220:223], v[24:27]
	v_mfma_f32_16x16x32_bf16 v[20:23], v[174:177], v[220:223], v[20:23]
	v_mfma_f32_16x16x32_bf16 v[8:11], v[166:169], v[228:231], v[8:11]
	v_mfma_f32_16x16x32_bf16 v[4:7], v[174:177], v[228:231], v[4:7]
	s_setprio 0
	s_barrier
	s_add_i32 s56, 0, 0x18000
	s_add_i32 s57, 0, 0x1c000
	v_add_u32_e32 v158, s56, v147
	v_add_u32_e32 v174, s57, v147
	ds_read_b128 v[142:145], v158
	ds_read_b128 v[150:153], v158 offset:1024
	ds_read_b128 v[154:157], v158 offset:2048
	ds_read_b128 v[158:161], v158 offset:3072
	ds_read_b128 v[162:165], v174
	ds_read_b128 v[166:169], v174 offset:1024
	ds_read_b128 v[170:173], v174 offset:2048
	ds_read_b128 v[174:177], v174 offset:3072
	s_add_u32 s28, s28, s10
	s_addc_u32 s29, s29, 0
	s_mov_b32 m0, s41
	v_lshl_add_u64 v[240:241], s[28:29], 0, v[136:137]
	ds_read_b128 v[178:181], v149 offset:32768
	ds_read_b128 v[182:185], v149 offset:33792
	ds_read_b128 v[186:189], v149 offset:34816
	ds_read_b128 v[190:193], v149 offset:35840
	ds_read_b128 v[204:207], v149 offset:36864
	ds_read_b128 v[220:223], v149 offset:37888
	ds_read_b128 v[224:227], v149 offset:38912
	ds_read_b128 v[228:231], v149 offset:39936
	global_load_lds_dwordx4 v[240:241], off
	v_lshl_add_u64 v[240:241], s[28:29], 0, v[134:135]
	s_mov_b32 m0, s42
	s_nop 0
	global_load_lds_dwordx4 v[240:241], off
	s_waitcnt vmcnt(8)
	s_waitcnt lgkmcnt(0)
	s_barrier
	s_setprio 1
	s_waitcnt lgkmcnt(0)
	v_mfma_f32_16x16x32_bf16 v[128:131], v[142:145], v[178:181], v[128:131]
	v_mfma_f32_16x16x32_bf16 v[124:127], v[154:157], v[178:181], v[124:127]
	v_mfma_f32_16x16x32_bf16 v[112:115], v[142:145], v[186:189], v[112:115]
	v_mfma_f32_16x16x32_bf16 v[108:111], v[154:157], v[186:189], v[108:111]
	v_mfma_f32_16x16x32_bf16 v[96:99], v[142:145], v[204:207], v[96:99]
	v_mfma_f32_16x16x32_bf16 v[92:95], v[154:157], v[204:207], v[92:95]
	v_mfma_f32_16x16x32_bf16 v[80:83], v[142:145], v[224:227], v[80:83]
	v_mfma_f32_16x16x32_bf16 v[76:79], v[154:157], v[224:227], v[76:79]
	v_mfma_f32_16x16x32_bf16 v[128:131], v[150:153], v[182:185], v[128:131]
	v_mfma_f32_16x16x32_bf16 v[124:127], v[158:161], v[182:185], v[124:127]
	v_mfma_f32_16x16x32_bf16 v[112:115], v[150:153], v[190:193], v[112:115]
	v_mfma_f32_16x16x32_bf16 v[108:111], v[158:161], v[190:193], v[108:111]
	v_mfma_f32_16x16x32_bf16 v[96:99], v[150:153], v[220:223], v[96:99]
	v_mfma_f32_16x16x32_bf16 v[92:95], v[158:161], v[220:223], v[92:95]
	v_mfma_f32_16x16x32_bf16 v[80:83], v[150:153], v[228:231], v[80:83]
	v_mfma_f32_16x16x32_bf16 v[76:79], v[158:161], v[228:231], v[76:79]
	s_setprio 0
	s_setprio 1
	v_mfma_f32_16x16x32_bf16 v[120:123], v[162:165], v[178:181], v[120:123]
	v_mfma_f32_16x16x32_bf16 v[116:119], v[170:173], v[178:181], v[116:119]
	v_mfma_f32_16x16x32_bf16 v[104:107], v[162:165], v[186:189], v[104:107]
	v_mfma_f32_16x16x32_bf16 v[100:103], v[170:173], v[186:189], v[100:103]
	v_mfma_f32_16x16x32_bf16 v[88:91], v[162:165], v[204:207], v[88:91]
	v_mfma_f32_16x16x32_bf16 v[84:87], v[170:173], v[204:207], v[84:87]
	v_mfma_f32_16x16x32_bf16 v[72:75], v[162:165], v[224:227], v[72:75]
	v_mfma_f32_16x16x32_bf16 v[68:71], v[170:173], v[224:227], v[68:71]
	v_mfma_f32_16x16x32_bf16 v[120:123], v[166:169], v[182:185], v[120:123]
	v_mfma_f32_16x16x32_bf16 v[116:119], v[174:177], v[182:185], v[116:119]
	v_mfma_f32_16x16x32_bf16 v[104:107], v[166:169], v[190:193], v[104:107]
	v_mfma_f32_16x16x32_bf16 v[100:103], v[174:177], v[190:193], v[100:103]
	v_mfma_f32_16x16x32_bf16 v[88:91], v[166:169], v[220:223], v[88:91]
	v_mfma_f32_16x16x32_bf16 v[84:87], v[174:177], v[220:223], v[84:87]
	v_mfma_f32_16x16x32_bf16 v[72:75], v[166:169], v[228:231], v[72:75]
	v_mfma_f32_16x16x32_bf16 v[68:71], v[174:177], v[228:231], v[68:71]
	s_setprio 0
	s_barrier
; #define PG8_STAGE(bufoff, gbase, voff) do { _Pragma("unroll") for (int _i = 0; _i < 2; ++_i) \
;         __builtin_amdgcn_global_load_lds((const unsigned*)((const char*)(gbase) + (voff)[_i]), (PG8_LAS unsigned*)(lds + (bufoff) + ldsw + _i * 8192), 16, 0, 0); } while (0)
; #define PG8_LDA(dst, b, h) do { _Pragma("unroll") for (int m = 0; m < 4; ++m) _Pragma("unroll") for (int k = 0; k < 2; ++k) dst[m][k] = *(const PG8_LAS bf16x8*)(lds + PG8_SA(b, h) + aoff + m * 2048 + k * 1024); } while (0)
; #define PG8_MMA(ai, bj, At, Bt) do { __builtin_amdgcn_s_setprio(1); _Pragma("unroll") for (int m = 0; m < 4; ++m) _Pragma("unroll") for (int n = 0; n < 2; ++n) _Pragma("unroll") for (int k = 0; k < 2; ++k) \
;         acc[ai][bj][m][n] = __builtin_amdgcn_mfma_f32_16x16x32_bf16(Bt[n][k], At[m][k], acc[ai][bj][m][n], 0, 0, 0); __builtin_amdgcn_s_setprio(0); } while (0)
; #define PG8_WAIT_V(n) asm volatile("s_waitcnt vmcnt(" #n ")" ::: "memory")
; #define PG8_WAIT_L(n) asm volatile("s_waitcnt lgkmcnt(" #n ")" ::: "memory")
; #define PG8_BAR __builtin_amdgcn_s_barrier()
; #define PG8_SCHED __builtin_amdgcn_sched_barrier(0)
; template <class Epi, class Sched, bool ALIGN_EPI = false, bool SP2 = false>
; __device__ __forceinline__ void gemm_phase(PG8_LAS unsigned char* lds, const Gemm g, const Sched& S, const Epi& E) {
;     ...
;             PG8_WAIT_V(8); PG8_WAIT_L(0); PG8_BAR; PG8_MMA(0, 0, At, B0); PG8_MMA(0, 1, At, B1); PG8_BAR; PG8_SCHED;
;             PG8_LDA(At, 1, 1); PG8_STAGE(PG8_SB(1, 0), b3, voffB); PG8_STAGE(PG8_SB(1, 1), b3 + hstep, voffB); PG8_STAGE(PG8_SA(1, 0), a3, voffA);
;             PG8_WAIT_V(8); PG8_WAIT_L(0); PG8_BAR; PG8_MMA(1, 0, At, B0); PG8_MMA(1, 1, At, B1); PG8_BAR; PG8_SCHED;
	s_add_i32 s28, s56, s31
	v_lshl_add_u64 v[194:195], v[194:195], 0, s[92:93]
	s_mov_b32 m0, s28
	ds_read_b128 v[178:181], v149 offset:49152
	ds_read_b128 v[182:185], v149 offset:50176
	ds_read_b128 v[186:189], v149 offset:51200
	ds_read_b128 v[190:193], v149 offset:52224
	ds_read_b128 v[204:207], v149 offset:53248
	ds_read_b128 v[220:223], v149 offset:54272
	ds_read_b128 v[224:227], v149 offset:55296
	ds_read_b128 v[228:231], v149 offset:56320
	global_load_lds_dwordx4 v[194:195], off
	v_lshl_add_u64 v[194:195], v[196:197], 0, s[92:93]
	s_add_i32 m0, s28, 0x2000
	s_add_i32 s28, s57, s31
	global_load_lds_dwordx4 v[194:195], off
	v_lshl_add_u64 v[194:195], v[232:233], 0, s[92:93]
	s_mov_b32 m0, s28
	s_nop 0
	global_load_lds_dwordx4 v[194:195], off
	v_lshl_add_u64 v[194:195], v[234:235], 0, s[92:93]
	s_add_i32 m0, s28, 0x2000
	s_nop 0
	global_load_lds_dwordx4 v[194:195], off
	v_lshl_add_u64 v[194:195], v[236:237], 0, s[92:93]
	s_mov_b32 m0, s45
	s_nop 0
	global_load_lds_dwordx4 v[194:195], off
	v_lshl_add_u64 v[194:195], v[238:239], 0, s[92:93]
	s_mov_b32 m0, s46
	s_nop 0
	global_load_lds_dwordx4 v[194:195], off
	s_waitcnt vmcnt(8)
	s_waitcnt lgkmcnt(0)
	s_barrier
	s_setprio 1
	s_waitcnt lgkmcnt(0)
	v_mfma_f32_16x16x32_bf16 v[64:67], v[142:145], v[178:181], v[64:67]
	v_mfma_f32_16x16x32_bf16 v[60:63], v[154:157], v[178:181], v[60:63]
	v_mfma_f32_16x16x32_bf16 v[48:51], v[142:145], v[186:189], v[48:51]
	v_mfma_f32_16x16x32_bf16 v[44:47], v[154:157], v[186:189], v[44:47]
	v_mfma_f32_16x16x32_bf16 v[32:35], v[142:145], v[204:207], v[32:35]
	v_mfma_f32_16x16x32_bf16 v[28:31], v[154:157], v[204:207], v[28:31]
	v_mfma_f32_16x16x32_bf16 v[16:19], v[142:145], v[224:227], v[16:19]
	v_mfma_f32_16x16x32_bf16 v[12:15], v[154:157], v[224:227], v[12:15]
	v_mfma_f32_16x16x32_bf16 v[64:67], v[150:153], v[182:185], v[64:67]
	v_mfma_f32_16x16x32_bf16 v[60:63], v[158:161], v[182:185], v[60:63]
	v_mfma_f32_16x16x32_bf16 v[48:51], v[150:153], v[190:193], v[48:51]
	v_mfma_f32_16x16x32_bf16 v[44:47], v[158:161], v[190:193], v[44:47]
	v_mfma_f32_16x16x32_bf16 v[32:35], v[150:153], v[220:223], v[32:35]
	v_mfma_f32_16x16x32_bf16 v[28:31], v[158:161], v[220:223], v[28:31]
	v_mfma_f32_16x16x32_bf16 v[16:19], v[150:153], v[228:231], v[16:19]
	v_mfma_f32_16x16x32_bf16 v[12:15], v[158:161], v[228:231], v[12:15]
	s_setprio 0
	s_setprio 1
	v_mfma_f32_16x16x32_bf16 v[56:59], v[162:165], v[178:181], v[56:59]
	v_mfma_f32_16x16x32_bf16 v[52:55], v[170:173], v[178:181], v[52:55]
	v_mfma_f32_16x16x32_bf16 v[40:43], v[162:165], v[186:189], v[40:43]
	v_mfma_f32_16x16x32_bf16 v[36:39], v[170:173], v[186:189], v[36:39]
	v_mfma_f32_16x16x32_bf16 v[24:27], v[162:165], v[204:207], v[24:27]
	v_mfma_f32_16x16x32_bf16 v[20:23], v[170:173], v[204:207], v[20:23]
	v_mfma_f32_16x16x32_bf16 v[8:11], v[162:165], v[224:227], v[8:11]
	v_mfma_f32_16x16x32_bf16 v[4:7], v[170:173], v[224:227], v[4:7]
	v_mfma_f32_16x16x32_bf16 v[56:59], v[166:169], v[182:185], v[56:59]
	v_mfma_f32_16x16x32_bf16 v[52:55], v[174:177], v[182:185], v[52:55]
	v_mfma_f32_16x16x32_bf16 v[40:43], v[166:169], v[190:193], v[40:43]
	v_mfma_f32_16x16x32_bf16 v[36:39], v[174:177], v[190:193], v[36:39]
	v_mfma_f32_16x16x32_bf16 v[24:27], v[166:169], v[220:223], v[24:27]
	v_mfma_f32_16x16x32_bf16 v[20:23], v[174:177], v[220:223], v[20:23]
	v_mfma_f32_16x16x32_bf16 v[8:11], v[166:169], v[228:231], v[8:11]
	v_mfma_f32_16x16x32_bf16 v[4:7], v[174:177], v[228:231], v[4:7]
	s_add_u32 s26, s26, 0x100
	s_addc_u32 s27, s27, 0
	s_add_u32 s33, s33, 0x100
	s_addc_u32 s54, s54, 0
	s_cmp_ge_u32 s55, s44
	s_mov_b32 s28, s55
	s_setprio 0
	s_barrier
	s_cbranch_scc0 .LBB0_638
	s_and_b64 vcc, exec, s[22:23]
	s_cbranch_vccz .LBB0_641
	s_barrier

; #define PG8_STAGE(bufoff, gbase, voff) do { _Pragma("unroll") for (int _i = 0; _i < 2; ++_i) \
;         __builtin_amdgcn_global_load_lds((const unsigned*)((const char*)(gbase) + (voff)[_i]), (PG8_LAS unsigned*)(lds + (bufoff) + ldsw + _i * 8192), 16, 0, 0); } while (0)
; #define PG8_LDA(dst, b, h) do { _Pragma("unroll") for (int m = 0; m < 4; ++m) _Pragma("unroll") for (int k = 0; k < 2; ++k) dst[m][k] = *(const PG8_LAS bf16x8*)(lds + PG8_SA(b, h) + aoff + m * 2048 + k * 1024); } while (0)
; #define PG8_LDB(dst, b, h) do { _Pragma("unroll") for (int n = 0; n < 2; ++n) _Pragma("unroll") for (int k = 0; k < 2; ++k) dst[n][k] = *(const PG8_LAS bf16x8*)(lds + PG8_SB(b, h) + boff + n * 2048 + k * 1024); } while (0)
; #define PG8_MMA(ai, bj, At, Bt) do { __builtin_amdgcn_s_setprio(1); _Pragma("unroll") for (int m = 0; m < 4; ++m) _Pragma("unroll") for (int n = 0; n < 2; ++n) _Pragma("unroll") for (int k = 0; k < 2; ++k) \
;         acc[ai][bj][m][n] = __builtin_amdgcn_mfma_f32_16x16x32_bf16(Bt[n][k], At[m][k], acc[ai][bj][m][n], 0, 0, 0); __builtin_amdgcn_s_setprio(0); } while (0)
; #define PG8_WAIT_V(n) asm volatile("s_waitcnt vmcnt(" #n ")" ::: "memory")
; #define PG8_WAIT_L(n) asm volatile("s_waitcnt lgkmcnt(" #n ")" ::: "memory")
; #define PG8_BAR __builtin_amdgcn_s_barrier()
; #define PG8_SCHED __builtin_amdgcn_sched_barrier(0)
; template <class Epi, class Sched, bool ALIGN_EPI = false, bool SP2 = false>
; __device__ __forceinline__ void gemm_phase(PG8_LAS unsigned char* lds, const Gemm g, const Sched& S, const Epi& E) {
;     ...
;             const char* a1 = cA + (size_t)(t + 1) * kstep;
;             const char* a2 = last ? nA : cA + (size_t)(t + 2) * kstep; const char* b2 = last ? nB : cB + (size_t)(t + 2) * kstep;
;             const char* a3 = a2 + kstep; const char* b3 = b2 + kstep;
;             if (last && has_next) S.a_ready(nxt);
;             if constexpr (SP2) {
;             PG8_LDB(B0, 0, 0); PG8_LDB(B1, 0, 1); PG8_SCHED; PG8_LDA(At, 0, 0); PG8_STAGE(PG8_SA(1, 1), a1 + hstep, voffA);
;             PG8_WAIT_V(8); PG8_WAIT_L(0); PG8_BAR; PG8_MMA(0, 0, At, B0); PG8_MMA(0, 1, At, B1); PG8_BAR; PG8_SCHED;
;             PG8_LDA(At, 0, 1); PG8_STAGE(PG8_SB(0, 0), b2, voffB); PG8_STAGE(PG8_SB(0, 1), b2 + hstep, voffB); PG8_STAGE(PG8_SA(0, 0), a2, voffA);
.LBB0_685:
	s_add_u32 s44, s42, 0xfffc0080
	s_addc_u32 s45, s43, -1
	s_add_i32 s69, 0, 0x10000
	s_cmp_eq_u32 s68, 12
	s_cselect_b32 s47, s33, s45
	s_cselect_b32 s46, s35, s44
	s_cselect_b32 s45, s31, s67
	s_cselect_b32 s44, s65, s66
	s_add_i32 s73, 0, 0x14000
	v_add_u32_e32 v158, s69, v147
	v_add_u32_e32 v174, s73, v147
	ds_read_b128 v[142:145], v158
	ds_read_b128 v[150:153], v158 offset:1024
	ds_read_b128 v[154:157], v158 offset:2048
	ds_read_b128 v[158:161], v158 offset:3072
	ds_read_b128 v[162:165], v174
	ds_read_b128 v[166:169], v174 offset:1024
	ds_read_b128 v[170:173], v174 offset:2048
	ds_read_b128 v[174:177], v174 offset:3072
	v_lshl_add_u64 v[194:195], s[42:43], 0, v[138:139]
	s_add_i32 m0, s58, 0xc000
	ds_read_b128 v[178:181], v149
	ds_read_b128 v[182:185], v149 offset:1024
	ds_read_b128 v[186:189], v149 offset:2048
	ds_read_b128 v[190:193], v149 offset:3072
	ds_read_b128 v[204:207], v149 offset:4096
	ds_read_b128 v[220:223], v149 offset:5120
	ds_read_b128 v[224:227], v149 offset:6144
	ds_read_b128 v[228:231], v149 offset:7168
	global_load_lds_dwordx4 v[194:195], off
	v_lshl_add_u64 v[194:195], s[42:43], 0, v[140:141]
	s_add_i32 m0, s58, 0xe000
	s_nop 0
	global_load_lds_dwordx4 v[194:195], off
	s_waitcnt vmcnt(8)
	s_waitcnt lgkmcnt(0)
	s_barrier
	s_setprio 1
	s_waitcnt lgkmcnt(0)
	v_mfma_f32_16x16x32_bf16 v[128:131], v[142:145], v[178:181], v[128:131]
	v_mfma_f32_16x16x32_bf16 v[124:127], v[154:157], v[178:181], v[124:127]
	v_mfma_f32_16x16x32_bf16 v[112:115], v[142:145], v[186:189], v[112:115]
	v_mfma_f32_16x16x32_bf16 v[108:111], v[154:157], v[186:189], v[108:111]
	v_mfma_f32_16x16x32_bf16 v[96:99], v[142:145], v[204:207], v[96:99]
	v_mfma_f32_16x16x32_bf16 v[92:95], v[154:157], v[204:207], v[92:95]
	v_mfma_f32_16x16x32_bf16 v[80:83], v[142:145], v[224:227], v[80:83]
	v_mfma_f32_16x16x32_bf16 v[76:79], v[154:157], v[224:227], v[76:79]
	v_mfma_f32_16x16x32_bf16 v[128:131], v[150:153], v[182:185], v[128:131]
	v_mfma_f32_16x16x32_bf16 v[124:127], v[158:161], v[182:185], v[124:127]
	v_mfma_f32_16x16x32_bf16 v[112:115], v[150:153], v[190:193], v[112:115]
	v_mfma_f32_16x16x32_bf16 v[108:111], v[158:161], v[190:193], v[108:111]
	v_mfma_f32_16x16x32_bf16 v[96:99], v[150:153], v[220:223], v[96:99]
	v_mfma_f32_16x16x32_bf16 v[92:95], v[158:161], v[220:223], v[92:95]
	v_mfma_f32_16x16x32_bf16 v[80:83], v[150:153], v[228:231], v[80:83]
	v_mfma_f32_16x16x32_bf16 v[76:79], v[158:161], v[228:231], v[76:79]
	s_setprio 0
	s_setprio 1
	v_mfma_f32_16x16x32_bf16 v[120:123], v[162:165], v[178:181], v[120:123]
	v_mfma_f32_16x16x32_bf16 v[116:119], v[170:173], v[178:181], v[116:119]
	v_mfma_f32_16x16x32_bf16 v[104:107], v[162:165], v[186:189], v[104:107]
	v_mfma_f32_16x16x32_bf16 v[100:103], v[170:173], v[186:189], v[100:103]
	v_mfma_f32_16x16x32_bf16 v[88:91], v[162:165], v[204:207], v[88:91]
	v_mfma_f32_16x16x32_bf16 v[84:87], v[170:173], v[204:207], v[84:87]
	v_mfma_f32_16x16x32_bf16 v[72:75], v[162:165], v[224:227], v[72:75]
	v_mfma_f32_16x16x32_bf16 v[68:71], v[170:173], v[224:227], v[68:71]
	v_mfma_f32_16x16x32_bf16 v[120:123], v[166:169], v[182:185], v[120:123]
	v_mfma_f32_16x16x32_bf16 v[116:119], v[174:177], v[182:185], v[116:119]
	v_mfma_f32_16x16x32_bf16 v[104:107], v[166:169], v[190:193], v[104:107]
	v_mfma_f32_16x16x32_bf16 v[100:103], v[174:177], v[190:193], v[100:103]
	v_mfma_f32_16x16x32_bf16 v[88:91], v[166:169], v[220:223], v[88:91]
	v_mfma_f32_16x16x32_bf16 v[84:87], v[174:177], v[220:223], v[84:87]
	v_mfma_f32_16x16x32_bf16 v[72:75], v[166:169], v[228:231], v[72:75]
	v_mfma_f32_16x16x32_bf16 v[68:71], v[174:177], v[228:231], v[68:71]
	s_setprio 0
	s_barrier
	s_add_i32 s69, s69, s56
	v_lshl_add_u64 v[194:195], s[44:45], 0, v[2:3]
	s_mov_b32 m0, s69
	ds_read_b128 v[178:181], v149 offset:16384
	ds_read_b128 v[182:185], v149 offset:17408
	ds_read_b128 v[186:189], v149 offset:18432
	ds_read_b128 v[190:193], v149 offset:19456
	ds_read_b128 v[204:207], v149 offset:20480
	ds_read_b128 v[220:223], v149 offset:21504
	ds_read_b128 v[224:227], v149 offset:22528
	ds_read_b128 v[228:231], v149 offset:23552
	global_load_lds_dwordx4 v[194:195], off
	s_add_i32 m0, s69, 0x2000
	s_add_u32 s70, s44, 0x40000
	v_lshl_add_u64 v[196:197], s[44:45], 0, v[136:137]
	s_addc_u32 s71, s45, 0
	s_add_i32 s69, s73, s56
	global_load_lds_dwordx4 v[196:197], off
	v_lshl_add_u64 v[232:233], s[70:71], 0, v[2:3]
	s_mov_b32 m0, s69
	v_lshl_add_u64 v[234:235], s[46:47], 0, v[134:135]
	global_load_lds_dwordx4 v[232:233], off
	v_lshl_add_u64 v[232:233], s[70:71], 0, v[136:137]
	s_add_i32 m0, s69, 0x2000
	s_nop 0
	global_load_lds_dwordx4 v[232:233], off
	v_lshl_add_u64 v[232:233], s[46:47], 0, v[132:133]
	s_mov_b32 m0, s58
	s_nop 0
	global_load_lds_dwordx4 v[232:233], off
	s_mov_b32 m0, s59
	s_nop 0
	global_load_lds_dwordx4 v[234:235], off
	s_waitcnt vmcnt(8)
	s_waitcnt lgkmcnt(0)
	s_barrier
; #define PG8_STAGE(bufoff, gbase, voff) do { _Pragma("unroll") for (int _i = 0; _i < 2; ++_i) \
;         __builtin_amdgcn_global_load_lds((const unsigned*)((const char*)(gbase) + (voff)[_i]), (PG8_LAS unsigned*)(lds + (bufoff) + ldsw + _i * 8192), 16, 0, 0); } while (0)
; #define PG8_LDA(dst, b, h) do { _Pragma("unroll") for (int m = 0; m < 4; ++m) _Pragma("unroll") for (int k = 0; k < 2; ++k) dst[m][k] = *(const PG8_LAS bf16x8*)(lds + PG8_SA(b, h) + aoff + m * 2048 + k * 1024); } while (0)
; #define PG8_LDB(dst, b, h) do { _Pragma("unroll") for (int n = 0; n < 2; ++n) _Pragma("unroll") for (int k = 0; k < 2; ++k) dst[n][k] = *(const PG8_LAS bf16x8*)(lds + PG8_SB(b, h) + boff + n * 2048 + k * 1024); } while (0)
; #define PG8_MMA(ai, bj, At, Bt) do { __builtin_amdgcn_s_setprio(1); _Pragma("unroll") for (int m = 0; m < 4; ++m) _Pragma("unroll") for (int n = 0; n < 2; ++n) _Pragma("unroll") for (int k = 0; k < 2; ++k) \
;         acc[ai][bj][m][n] = __builtin_amdgcn_mfma_f32_16x16x32_bf16(Bt[n][k], At[m][k], acc[ai][bj][m][n], 0, 0, 0); __builtin_amdgcn_s_setprio(0); } while (0)
; #define PG8_WAIT_V(n) asm volatile("s_waitcnt vmcnt(" #n ")" ::: "memory")
; #define PG8_WAIT_L(n) asm volatile("s_waitcnt lgkmcnt(" #n ")" ::: "memory")
; #define PG8_BAR __builtin_amdgcn_s_barrier()
; #define PG8_SCHED __builtin_amdgcn_sched_barrier(0)
; template <class Epi, class Sched, bool ALIGN_EPI = false, bool SP2 = false>
; __device__ __forceinline__ void gemm_phase(PG8_LAS unsigned char* lds, const Gemm g, const Sched& S, const Epi& E) {
;     ...
;             PG8_WAIT_V(8); PG8_WAIT_L(0); PG8_BAR; PG8_MMA(1, 0, At, B0); PG8_MMA(1, 1, At, B1); PG8_BAR; PG8_SCHED;
;             PG8_LDB(B0, 1, 0); PG8_LDB(B1, 1, 1); PG8_SCHED; PG8_LDA(At, 1, 0); PG8_STAGE(PG8_SA(0, 1), a2 + hstep, voffA);
;             PG8_WAIT_V(8); PG8_WAIT_L(0); PG8_BAR; PG8_MMA(0, 0, At, B0); PG8_MMA(0, 1, At, B1); PG8_BAR; PG8_SCHED;
	s_setprio 1
	s_waitcnt lgkmcnt(0)
	v_mfma_f32_16x16x32_bf16 v[64:67], v[142:145], v[178:181], v[64:67]
	v_mfma_f32_16x16x32_bf16 v[60:63], v[154:157], v[178:181], v[60:63]
	v_mfma_f32_16x16x32_bf16 v[48:51], v[142:145], v[186:189], v[48:51]
	v_mfma_f32_16x16x32_bf16 v[44:47], v[154:157], v[186:189], v[44:47]
	v_mfma_f32_16x16x32_bf16 v[32:35], v[142:145], v[204:207], v[32:35]
	v_mfma_f32_16x16x32_bf16 v[28:31], v[154:157], v[204:207], v[28:31]
	v_mfma_f32_16x16x32_bf16 v[16:19], v[142:145], v[224:227], v[16:19]
	v_mfma_f32_16x16x32_bf16 v[12:15], v[154:157], v[224:227], v[12:15]
	v_mfma_f32_16x16x32_bf16 v[64:67], v[150:153], v[182:185], v[64:67]
	v_mfma_f32_16x16x32_bf16 v[60:63], v[158:161], v[182:185], v[60:63]
	v_mfma_f32_16x16x32_bf16 v[48:51], v[150:153], v[190:193], v[48:51]
	v_mfma_f32_16x16x32_bf16 v[44:47], v[158:161], v[190:193], v[44:47]
	v_mfma_f32_16x16x32_bf16 v[32:35], v[150:153], v[220:223], v[32:35]
	v_mfma_f32_16x16x32_bf16 v[28:31], v[158:161], v[220:223], v[28:31]
	v_mfma_f32_16x16x32_bf16 v[16:19], v[150:153], v[228:231], v[16:19]
	v_mfma_f32_16x16x32_bf16 v[12:15], v[158:161], v[228:231], v[12:15]
	s_setprio 0
	s_setprio 1
	v_mfma_f32_16x16x32_bf16 v[56:59], v[162:165], v[178:181], v[56:59]
	v_mfma_f32_16x16x32_bf16 v[52:55], v[170:173], v[178:181], v[52:55]
	v_mfma_f32_16x16x32_bf16 v[40:43], v[162:165], v[186:189], v[40:43]
	v_mfma_f32_16x16x32_bf16 v[36:39], v[170:173], v[186:189], v[36:39]
	v_mfma_f32_16x16x32_bf16 v[24:27], v[162:165], v[204:207], v[24:27]
	v_mfma_f32_16x16x32_bf16 v[20:23], v[170:173], v[204:207], v[20:23]
	v_mfma_f32_16x16x32_bf16 v[8:11], v[162:165], v[224:227], v[8:11]
	v_mfma_f32_16x16x32_bf16 v[4:7], v[170:173], v[224:227], v[4:7]
	v_mfma_f32_16x16x32_bf16 v[56:59], v[166:169], v[182:185], v[56:59]
	v_mfma_f32_16x16x32_bf16 v[52:55], v[174:177], v[182:185], v[52:55]
	v_mfma_f32_16x16x32_bf16 v[40:43], v[166:169], v[190:193], v[40:43]
	v_mfma_f32_16x16x32_bf16 v[36:39], v[174:177], v[190:193], v[36:39]
	v_mfma_f32_16x16x32_bf16 v[24:27], v[166:169], v[220:223], v[24:27]
	v_mfma_f32_16x16x32_bf16 v[20:23], v[174:177], v[220:223], v[20:23]
	v_mfma_f32_16x16x32_bf16 v[8:11], v[166:169], v[228:231], v[8:11]
	v_mfma_f32_16x16x32_bf16 v[4:7], v[174:177], v[228:231], v[4:7]
	s_setprio 0
	s_barrier
	s_add_i32 s69, 0, 0x18000
	s_add_i32 s70, 0, 0x1c000
	v_add_u32_e32 v158, s69, v147
	v_add_u32_e32 v174, s70, v147
	ds_read_b128 v[142:145], v158
	ds_read_b128 v[150:153], v158 offset:1024
	ds_read_b128 v[154:157], v158 offset:2048
	ds_read_b128 v[158:161], v158 offset:3072
	ds_read_b128 v[162:165], v174
	ds_read_b128 v[166:169], v174 offset:1024
	ds_read_b128 v[170:173], v174 offset:2048
	ds_read_b128 v[174:177], v174 offset:3072
	s_add_u32 s46, s46, 0x40000
	s_addc_u32 s47, s47, 0
	s_mov_b32 m0, s60
	v_lshl_add_u64 v[236:237], s[46:47], 0, v[132:133]
	ds_read_b128 v[178:181], v149 offset:32768
	ds_read_b128 v[182:185], v149 offset:33792
	ds_read_b128 v[186:189], v149 offset:34816
	ds_read_b128 v[190:193], v149 offset:35840
	ds_read_b128 v[204:207], v149 offset:36864
	ds_read_b128 v[220:223], v149 offset:37888
	ds_read_b128 v[224:227], v149 offset:38912
	ds_read_b128 v[228:231], v149 offset:39936
	global_load_lds_dwordx4 v[236:237], off
	v_lshl_add_u64 v[236:237], s[46:47], 0, v[134:135]
	s_mov_b32 m0, s61
	s_nop 0
	global_load_lds_dwordx4 v[236:237], off
	s_waitcnt vmcnt(8)
	s_waitcnt lgkmcnt(0)
	s_barrier
	s_setprio 1
	s_waitcnt lgkmcnt(0)
	v_mfma_f32_16x16x32_bf16 v[128:131], v[142:145], v[178:181], v[128:131]
	v_mfma_f32_16x16x32_bf16 v[124:127], v[154:157], v[178:181], v[124:127]
	v_mfma_f32_16x16x32_bf16 v[112:115], v[142:145], v[186:189], v[112:115]
	v_mfma_f32_16x16x32_bf16 v[108:111], v[154:157], v[186:189], v[108:111]
	v_mfma_f32_16x16x32_bf16 v[96:99], v[142:145], v[204:207], v[96:99]
	v_mfma_f32_16x16x32_bf16 v[92:95], v[154:157], v[204:207], v[92:95]
	v_mfma_f32_16x16x32_bf16 v[80:83], v[142:145], v[224:227], v[80:83]
	v_mfma_f32_16x16x32_bf16 v[76:79], v[154:157], v[224:227], v[76:79]
	v_mfma_f32_16x16x32_bf16 v[128:131], v[150:153], v[182:185], v[128:131]
	v_mfma_f32_16x16x32_bf16 v[124:127], v[158:161], v[182:185], v[124:127]
	v_mfma_f32_16x16x32_bf16 v[112:115], v[150:153], v[190:193], v[112:115]
	v_mfma_f32_16x16x32_bf16 v[108:111], v[158:161], v[190:193], v[108:111]
	v_mfma_f32_16x16x32_bf16 v[96:99], v[150:153], v[220:223], v[96:99]
	v_mfma_f32_16x16x32_bf16 v[92:95], v[158:161], v[220:223], v[92:95]
	v_mfma_f32_16x16x32_bf16 v[80:83], v[150:153], v[228:231], v[80:83]
	v_mfma_f32_16x16x32_bf16 v[76:79], v[158:161], v[228:231], v[76:79]
	s_setprio 0
	s_setprio 1
	v_mfma_f32_16x16x32_bf16 v[120:123], v[162:165], v[178:181], v[120:123]
	v_mfma_f32_16x16x32_bf16 v[116:119], v[170:173], v[178:181], v[116:119]
	v_mfma_f32_16x16x32_bf16 v[104:107], v[162:165], v[186:189], v[104:107]
	v_mfma_f32_16x16x32_bf16 v[100:103], v[170:173], v[186:189], v[100:103]
	v_mfma_f32_16x16x32_bf16 v[88:91], v[162:165], v[204:207], v[88:91]
	v_mfma_f32_16x16x32_bf16 v[84:87], v[170:173], v[204:207], v[84:87]
	v_mfma_f32_16x16x32_bf16 v[72:75], v[162:165], v[224:227], v[72:75]
	v_mfma_f32_16x16x32_bf16 v[68:71], v[170:173], v[224:227], v[68:71]
	v_mfma_f32_16x16x32_bf16 v[120:123], v[166:169], v[182:185], v[120:123]
	v_mfma_f32_16x16x32_bf16 v[116:119], v[174:177], v[182:185], v[116:119]
	v_mfma_f32_16x16x32_bf16 v[104:107], v[166:169], v[190:193], v[104:107]
	v_mfma_f32_16x16x32_bf16 v[100:103], v[174:177], v[190:193], v[100:103]
	v_mfma_f32_16x16x32_bf16 v[88:91], v[166:169], v[220:223], v[88:91]
	v_mfma_f32_16x16x32_bf16 v[84:87], v[174:177], v[220:223], v[84:87]
	v_mfma_f32_16x16x32_bf16 v[72:75], v[166:169], v[228:231], v[72:75]
	v_mfma_f32_16x16x32_bf16 v[68:71], v[174:177], v[228:231], v[68:71]
	s_setprio 0
	s_barrier
; #define PG8_STAGE(bufoff, gbase, voff) do { _Pragma("unroll") for (int _i = 0; _i < 2; ++_i) \
;         __builtin_amdgcn_global_load_lds((const unsigned*)((const char*)(gbase) + (voff)[_i]), (PG8_LAS unsigned*)(lds + (bufoff) + ldsw + _i * 8192), 16, 0, 0); } while (0)
; #define PG8_LDA(dst, b, h) do { _Pragma("unroll") for (int m = 0; m < 4; ++m) _Pragma("unroll") for (int k = 0; k < 2; ++k) dst[m][k] = *(const PG8_LAS bf16x8*)(lds + PG8_SA(b, h) + aoff + m * 2048 + k * 1024); } while (0)
; #define PG8_MMA(ai, bj, At, Bt) do { __builtin_amdgcn_s_setprio(1); _Pragma("unroll") for (int m = 0; m < 4; ++m) _Pragma("unroll") for (int n = 0; n < 2; ++n) _Pragma("unroll") for (int k = 0; k < 2; ++k) \
;         acc[ai][bj][m][n] = __builtin_amdgcn_mfma_f32_16x16x32_bf16(Bt[n][k], At[m][k], acc[ai][bj][m][n], 0, 0, 0); __builtin_amdgcn_s_setprio(0); } while (0)
; #define PG8_WAIT_V(n) asm volatile("s_waitcnt vmcnt(" #n ")" ::: "memory")
; #define PG8_WAIT_L(n) asm volatile("s_waitcnt lgkmcnt(" #n ")" ::: "memory")
; #define PG8_BAR __builtin_amdgcn_s_barrier()
; #define PG8_SCHED __builtin_amdgcn_sched_barrier(0)
; template <class Epi, class Sched, bool ALIGN_EPI = false, bool SP2 = false>
; __device__ __forceinline__ void gemm_phase(PG8_LAS unsigned char* lds, const Gemm g, const Sched& S, const Epi& E) {
;     ...
;         for (int t = 0; t < nt; t += 2) {
;             const bool last = (t == nt - 2);
;     ...
;             PG8_LDA(At, 1, 1); PG8_STAGE(PG8_SB(1, 0), b3, voffB); PG8_STAGE(PG8_SB(1, 1), b3 + hstep, voffB); PG8_STAGE(PG8_SA(1, 0), a3, voffA);
;             PG8_WAIT_V(8); PG8_WAIT_L(0); PG8_BAR; PG8_MMA(1, 0, At, B0); PG8_MMA(1, 1, At, B1); PG8_BAR; PG8_SCHED;
	s_add_i32 s46, s69, s56
	v_lshl_add_u64 v[194:195], v[194:195], 0, s[92:93]
	s_mov_b32 m0, s46
	ds_read_b128 v[178:181], v149 offset:49152
	ds_read_b128 v[182:185], v149 offset:50176
	ds_read_b128 v[186:189], v149 offset:51200
	ds_read_b128 v[190:193], v149 offset:52224
	ds_read_b128 v[204:207], v149 offset:53248
	ds_read_b128 v[220:223], v149 offset:54272
	ds_read_b128 v[224:227], v149 offset:55296
	ds_read_b128 v[228:231], v149 offset:56320
	global_load_lds_dwordx4 v[194:195], off
	s_add_i32 m0, s46, 0x2000
	s_add_u32 s44, s44, 0x40080
	v_lshl_add_u64 v[194:195], v[196:197], 0, s[92:93]
	s_addc_u32 s45, s45, 0
	s_add_i32 s46, s70, s56
	global_load_lds_dwordx4 v[194:195], off
	v_lshl_add_u64 v[194:195], s[44:45], 0, v[2:3]
	s_mov_b32 m0, s46
	s_nop 0
	global_load_lds_dwordx4 v[194:195], off
	v_lshl_add_u64 v[194:195], s[44:45], 0, v[136:137]
	s_add_i32 m0, s46, 0x2000
	s_nop 0
	global_load_lds_dwordx4 v[194:195], off
	v_lshl_add_u64 v[194:195], v[232:233], 0, s[92:93]
	s_mov_b32 m0, s62
	s_nop 0
	global_load_lds_dwordx4 v[194:195], off
	v_lshl_add_u64 v[194:195], v[234:235], 0, s[92:93]
	s_mov_b32 m0, s63
	s_nop 0
	global_load_lds_dwordx4 v[194:195], off
	s_waitcnt vmcnt(8)
	s_waitcnt lgkmcnt(0)
	s_barrier
	s_setprio 1
	s_waitcnt lgkmcnt(0)
	v_mfma_f32_16x16x32_bf16 v[64:67], v[142:145], v[178:181], v[64:67]
	v_mfma_f32_16x16x32_bf16 v[60:63], v[154:157], v[178:181], v[60:63]
	v_mfma_f32_16x16x32_bf16 v[48:51], v[142:145], v[186:189], v[48:51]
	v_mfma_f32_16x16x32_bf16 v[44:47], v[154:157], v[186:189], v[44:47]
	v_mfma_f32_16x16x32_bf16 v[32:35], v[142:145], v[204:207], v[32:35]
	v_mfma_f32_16x16x32_bf16 v[28:31], v[154:157], v[204:207], v[28:31]
	v_mfma_f32_16x16x32_bf16 v[16:19], v[142:145], v[224:227], v[16:19]
	v_mfma_f32_16x16x32_bf16 v[12:15], v[154:157], v[224:227], v[12:15]
	v_mfma_f32_16x16x32_bf16 v[64:67], v[150:153], v[182:185], v[64:67]
	v_mfma_f32_16x16x32_bf16 v[60:63], v[158:161], v[182:185], v[60:63]
	v_mfma_f32_16x16x32_bf16 v[48:51], v[150:153], v[190:193], v[48:51]
	v_mfma_f32_16x16x32_bf16 v[44:47], v[158:161], v[190:193], v[44:47]
	v_mfma_f32_16x16x32_bf16 v[32:35], v[150:153], v[220:223], v[32:35]
	v_mfma_f32_16x16x32_bf16 v[28:31], v[158:161], v[220:223], v[28:31]
	v_mfma_f32_16x16x32_bf16 v[16:19], v[150:153], v[228:231], v[16:19]
	v_mfma_f32_16x16x32_bf16 v[12:15], v[158:161], v[228:231], v[12:15]
	s_setprio 0
	s_setprio 1
	v_mfma_f32_16x16x32_bf16 v[56:59], v[162:165], v[178:181], v[56:59]
	v_mfma_f32_16x16x32_bf16 v[52:55], v[170:173], v[178:181], v[52:55]
	v_mfma_f32_16x16x32_bf16 v[40:43], v[162:165], v[186:189], v[40:43]
	v_mfma_f32_16x16x32_bf16 v[36:39], v[170:173], v[186:189], v[36:39]
	v_mfma_f32_16x16x32_bf16 v[24:27], v[162:165], v[204:207], v[24:27]
	v_mfma_f32_16x16x32_bf16 v[20:23], v[170:173], v[204:207], v[20:23]
	v_mfma_f32_16x16x32_bf16 v[8:11], v[162:165], v[224:227], v[8:11]
	v_mfma_f32_16x16x32_bf16 v[4:7], v[170:173], v[224:227], v[4:7]
	v_mfma_f32_16x16x32_bf16 v[56:59], v[166:169], v[182:185], v[56:59]
	v_mfma_f32_16x16x32_bf16 v[52:55], v[174:177], v[182:185], v[52:55]
	v_mfma_f32_16x16x32_bf16 v[40:43], v[166:169], v[190:193], v[40:43]
	v_mfma_f32_16x16x32_bf16 v[36:39], v[174:177], v[190:193], v[36:39]
	v_mfma_f32_16x16x32_bf16 v[24:27], v[166:169], v[220:223], v[24:27]
	v_mfma_f32_16x16x32_bf16 v[20:23], v[174:177], v[220:223], v[20:23]
	v_mfma_f32_16x16x32_bf16 v[8:11], v[166:169], v[228:231], v[8:11]
	v_mfma_f32_16x16x32_bf16 v[4:7], v[174:177], v[228:231], v[4:7]
	s_add_i32 s68, s68, 2
	s_add_u32 s42, s42, 0x100
	s_addc_u32 s43, s43, 0
	s_add_u32 s66, s66, 0x100
	s_addc_u32 s67, s67, 0
	s_cmp_gt_u32 s68, 13
	s_setprio 0
	s_barrier
	s_cbranch_scc0 .LBB0_685
	s_and_b64 vcc, exec, s[28:29]
	s_cbranch_vccz .LBB0_688
	s_barrier
